# combination: cross-tile prefetch + v_cvt_pk epilogue rounding + de-serialised store ladder in the gemm_in / gemm_out tile code
# baseline (speedup 1.0000x reference)
.Lpfi_skip:
	v_add_u32_e32 v130, s1, v179
	s_movk_i32 s1, 0xa20
	v_ashrrev_i32_e32 v131, 31, v130
	v_cmp_gt_i32_e32 vcc, s1, v130
	v_lshl_add_u64 v[134:135], v[130:131], 1, s[60:61]
	s_nop 5
	v_cvt_pk_bf16_f32 v182, v112, v113
	s_barrier
	ds_write_b16 v156, v182
	ds_write_b16_d16_hi v156, v182 offset:144
	v_cvt_pk_bf16_f32 v183, v114, v115
	ds_write_b16 v156, v183 offset:288
	ds_write_b16_d16_hi v156, v183 offset:432
	v_cvt_pk_bf16_f32 v184, v116, v117
	ds_write_b16 v156, v184 offset:1152
	ds_write_b16_d16_hi v156, v184 offset:1296
	v_cvt_pk_bf16_f32 v185, v118, v119
	ds_write_b16 v156, v185 offset:1440
	ds_write_b16_d16_hi v156, v185 offset:1584
	v_cvt_pk_bf16_f32 v182, v120, v121
	ds_write_b16 v156, v182 offset:2304
	ds_write_b16_d16_hi v156, v182 offset:2448
	v_cvt_pk_bf16_f32 v183, v122, v123
	ds_write_b16 v156, v183 offset:2592
	ds_write_b16_d16_hi v156, v183 offset:2736
	v_cvt_pk_bf16_f32 v184, v124, v125
	ds_write_b16 v156, v184 offset:3456
	ds_write_b16_d16_hi v156, v184 offset:3600
	v_cvt_pk_bf16_f32 v185, v126, v127
	ds_write_b16 v156, v185 offset:3744
	ds_write_b16_d16_hi v156, v185 offset:3888
	v_cvt_pk_bf16_f32 v182, v96, v97
	ds_write_b16 v156, v182 offset:64
	ds_write_b16_d16_hi v156, v182 offset:208
	v_cvt_pk_bf16_f32 v183, v98, v99
	ds_write_b16 v156, v183 offset:352
	ds_write_b16_d16_hi v156, v183 offset:496
	v_cvt_pk_bf16_f32 v184, v100, v101
	ds_write_b16 v156, v184 offset:1216
	ds_write_b16_d16_hi v156, v184 offset:1360
	v_cvt_pk_bf16_f32 v185, v102, v103
	ds_write_b16 v156, v185 offset:1504
	ds_write_b16_d16_hi v156, v185 offset:1648
	v_cvt_pk_bf16_f32 v182, v104, v105
	ds_write_b16 v156, v182 offset:2368
	ds_write_b16_d16_hi v156, v182 offset:2512
	v_cvt_pk_bf16_f32 v183, v106, v107
	ds_write_b16 v156, v183 offset:2656
	ds_write_b16_d16_hi v156, v183 offset:2800
	v_cvt_pk_bf16_f32 v184, v108, v109
	ds_write_b16 v156, v184 offset:3520
	ds_write_b16_d16_hi v156, v184 offset:3664
	v_cvt_pk_bf16_f32 v185, v110, v111
	v_add_u32_e32 v136, s0, v153
	ds_write_b16 v156, v185 offset:3808
	ds_write_b16_d16_hi v156, v185 offset:3952
	s_and_saveexec_b64 s[0:1], vcc
	s_cbranch_execz .LBB0_242
	ds_read_b128 v[186:189], v170
	ds_read_b128 v[190:193], v170 offset:1152
	ds_read_b128 v[194:197], v170 offset:2304
	ds_read_b128 v[198:201], v170 offset:3456
	v_or_b32_e32 v202, v136, v157
	v_mad_i64_i32 v[202:203], s[10:11], v202, s33, v[134:135]
	v_or_b32_e32 v204, v136, v171
	v_mad_i64_i32 v[204:205], s[10:11], v204, s33, v[134:135]
	v_or_b32_e32 v206, v136, v252
	v_mad_i64_i32 v[206:207], s[10:11], v206, s33, v[134:135]
	v_or_b32_e32 v208, v136, v181
	v_mad_i64_i32 v[208:209], s[10:11], v208, s33, v[134:135]
	s_waitcnt lgkmcnt(3)
	global_store_dwordx4 v[202:203], v[186:189], off
	s_waitcnt lgkmcnt(2)
	global_store_dwordx4 v[204:205], v[190:193], off
	s_waitcnt lgkmcnt(1)
	global_store_dwordx4 v[206:207], v[194:197], off
	s_waitcnt lgkmcnt(0)
	global_store_dwordx4 v[208:209], v[198:201], off
.LBB0_242:
	s_or_b64 exec, exec, s[0:1]
	s_nop 0
	v_cvt_pk_bf16_f32 v182, v80, v81
	ds_write_b16 v156, v182
	ds_write_b16_d16_hi v156, v182 offset:144
	v_cvt_pk_bf16_f32 v183, v82, v83
	ds_write_b16 v156, v183 offset:288
	ds_write_b16_d16_hi v156, v183 offset:432
	v_cvt_pk_bf16_f32 v184, v84, v85
	ds_write_b16 v156, v184 offset:1152
	ds_write_b16_d16_hi v156, v184 offset:1296
	v_cvt_pk_bf16_f32 v185, v86, v87
	ds_write_b16 v156, v185 offset:1440
	ds_write_b16_d16_hi v156, v185 offset:1584
	v_cvt_pk_bf16_f32 v182, v88, v89
	ds_write_b16 v156, v182 offset:2304
	ds_write_b16_d16_hi v156, v182 offset:2448
	v_cvt_pk_bf16_f32 v183, v90, v91
	ds_write_b16 v156, v183 offset:2592
	ds_write_b16_d16_hi v156, v183 offset:2736
	v_cvt_pk_bf16_f32 v184, v92, v93
	ds_write_b16 v156, v184 offset:3456
	ds_write_b16_d16_hi v156, v184 offset:3600
	v_cvt_pk_bf16_f32 v185, v94, v95
	ds_write_b16 v156, v185 offset:3744
	ds_write_b16_d16_hi v156, v185 offset:3888
	v_cvt_pk_bf16_f32 v182, v64, v65
	ds_write_b16 v156, v182 offset:64
	ds_write_b16_d16_hi v156, v182 offset:208
	v_cvt_pk_bf16_f32 v183, v66, v67
	ds_write_b16 v156, v183 offset:352
	ds_write_b16_d16_hi v156, v183 offset:496
	v_cvt_pk_bf16_f32 v184, v68, v69
	ds_write_b16 v156, v184 offset:1216
	ds_write_b16_d16_hi v156, v184 offset:1360
	v_cvt_pk_bf16_f32 v185, v70, v71
	ds_write_b16 v156, v185 offset:1504
	ds_write_b16_d16_hi v156, v185 offset:1648
	v_cvt_pk_bf16_f32 v182, v72, v73
	ds_write_b16 v156, v182 offset:2368
	ds_write_b16_d16_hi v156, v182 offset:2512
	v_cvt_pk_bf16_f32 v183, v74, v75
	ds_write_b16 v156, v183 offset:2656
	ds_write_b16_d16_hi v156, v183 offset:2800
	v_cvt_pk_bf16_f32 v184, v76, v77
	ds_write_b16 v156, v184 offset:3520
	ds_write_b16_d16_hi v156, v184 offset:3664
	v_cvt_pk_bf16_f32 v185, v78, v79
	ds_write_b16 v156, v185 offset:3808
	ds_write_b16_d16_hi v156, v185 offset:3952
	s_and_saveexec_b64 s[0:1], vcc
	s_cbranch_execz .LBB0_244
	ds_read_b128 v[186:189], v170
	ds_read_b128 v[190:193], v170 offset:1152
	ds_read_b128 v[194:197], v170 offset:2304
	ds_read_b128 v[198:201], v170 offset:3456
	v_or_b32_e32 v70, 32, v136
	v_or_b32_e32 v202, v70, v157
	v_mad_i64_i32 v[202:203], s[10:11], v202, s33, v[134:135]
	v_or_b32_e32 v204, v70, v171
	v_mad_i64_i32 v[204:205], s[10:11], v204, s33, v[134:135]
	v_or_b32_e32 v206, v70, v252
	v_mad_i64_i32 v[206:207], s[10:11], v206, s33, v[134:135]
	v_or_b32_e32 v208, v70, v181
	v_mad_i64_i32 v[208:209], s[10:11], v208, s33, v[134:135]
	s_waitcnt lgkmcnt(3)
	global_store_dwordx4 v[202:203], v[186:189], off
	s_waitcnt lgkmcnt(2)
	global_store_dwordx4 v[204:205], v[190:193], off
	s_waitcnt lgkmcnt(1)
	global_store_dwordx4 v[206:207], v[194:197], off
	s_waitcnt lgkmcnt(0)
	global_store_dwordx4 v[208:209], v[198:201], off
.LBB0_244:
	s_or_b64 exec, exec, s[0:1]
	s_nop 0
	v_cvt_pk_bf16_f32 v182, v48, v49
	ds_write_b16 v156, v182
	ds_write_b16_d16_hi v156, v182 offset:144
	v_cvt_pk_bf16_f32 v183, v50, v51
	ds_write_b16 v156, v183 offset:288
	ds_write_b16_d16_hi v156, v183 offset:432
	v_cvt_pk_bf16_f32 v184, v52, v53
	ds_write_b16 v156, v184 offset:1152
	ds_write_b16_d16_hi v156, v184 offset:1296
	v_cvt_pk_bf16_f32 v185, v54, v55
	ds_write_b16 v156, v185 offset:1440
	ds_write_b16_d16_hi v156, v185 offset:1584
	v_cvt_pk_bf16_f32 v182, v56, v57
	ds_write_b16 v156, v182 offset:2304
	ds_write_b16_d16_hi v156, v182 offset:2448
	v_cvt_pk_bf16_f32 v183, v58, v59
	ds_write_b16 v156, v183 offset:2592
	ds_write_b16_d16_hi v156, v183 offset:2736
	v_cvt_pk_bf16_f32 v184, v60, v61
	ds_write_b16 v156, v184 offset:3456
	ds_write_b16_d16_hi v156, v184 offset:3600
	v_cvt_pk_bf16_f32 v185, v62, v63
	ds_write_b16 v156, v185 offset:3744
	ds_write_b16_d16_hi v156, v185 offset:3888
	v_cvt_pk_bf16_f32 v182, v32, v33
	ds_write_b16 v156, v182 offset:64
	ds_write_b16_d16_hi v156, v182 offset:208
	v_cvt_pk_bf16_f32 v183, v34, v35
	ds_write_b16 v156, v183 offset:352
	ds_write_b16_d16_hi v156, v183 offset:496
	v_cvt_pk_bf16_f32 v184, v36, v37
	ds_write_b16 v156, v184 offset:1216
	ds_write_b16_d16_hi v156, v184 offset:1360
	v_cvt_pk_bf16_f32 v185, v38, v39
	ds_write_b16 v156, v185 offset:1504
	ds_write_b16_d16_hi v156, v185 offset:1648
	v_cvt_pk_bf16_f32 v182, v40, v41
	ds_write_b16 v156, v182 offset:2368
	ds_write_b16_d16_hi v156, v182 offset:2512
	v_cvt_pk_bf16_f32 v183, v42, v43
	ds_write_b16 v156, v183 offset:2656
	ds_write_b16_d16_hi v156, v183 offset:2800
	v_cvt_pk_bf16_f32 v184, v44, v45
	ds_write_b16 v156, v184 offset:3520
	ds_write_b16_d16_hi v156, v184 offset:3664
	v_cvt_pk_bf16_f32 v185, v46, v47
	ds_write_b16 v156, v185 offset:3808
	ds_write_b16_d16_hi v156, v185 offset:3952
	s_and_saveexec_b64 s[0:1], vcc
	s_cbranch_execz .LBB0_246
	ds_read_b128 v[186:189], v170
	ds_read_b128 v[190:193], v170 offset:1152
	ds_read_b128 v[194:197], v170 offset:2304
	ds_read_b128 v[198:201], v170 offset:3456
	v_or_b32_e32 v38, 64, v136
	v_or_b32_e32 v202, v38, v157
	v_mad_i64_i32 v[202:203], s[10:11], v202, s33, v[134:135]
	v_or_b32_e32 v204, v38, v171
	v_mad_i64_i32 v[204:205], s[10:11], v204, s33, v[134:135]
	v_or_b32_e32 v206, v38, v252
	v_mad_i64_i32 v[206:207], s[10:11], v206, s33, v[134:135]
	v_or_b32_e32 v208, v38, v181
	v_mad_i64_i32 v[208:209], s[10:11], v208, s33, v[134:135]
	s_waitcnt lgkmcnt(3)
	global_store_dwordx4 v[202:203], v[186:189], off
	s_waitcnt lgkmcnt(2)
	global_store_dwordx4 v[204:205], v[190:193], off
	s_waitcnt lgkmcnt(1)
	global_store_dwordx4 v[206:207], v[194:197], off
	s_waitcnt lgkmcnt(0)
	global_store_dwordx4 v[208:209], v[198:201], off
.LBB0_246:
	s_or_b64 exec, exec, s[0:1]
	s_nop 0
	v_cvt_pk_bf16_f32 v182, v16, v17
	ds_write_b16 v156, v182
	ds_write_b16_d16_hi v156, v182 offset:144
	v_cvt_pk_bf16_f32 v183, v18, v19
	ds_write_b16 v156, v183 offset:288
	ds_write_b16_d16_hi v156, v183 offset:432
	v_cvt_pk_bf16_f32 v184, v20, v21
	ds_write_b16 v156, v184 offset:1152
	ds_write_b16_d16_hi v156, v184 offset:1296
	v_cvt_pk_bf16_f32 v185, v22, v23
	ds_write_b16 v156, v185 offset:1440
	ds_write_b16_d16_hi v156, v185 offset:1584
	v_cvt_pk_bf16_f32 v182, v24, v25
	ds_write_b16 v156, v182 offset:2304
	ds_write_b16_d16_hi v156, v182 offset:2448
	v_cvt_pk_bf16_f32 v183, v26, v27
	ds_write_b16 v156, v183 offset:2592
	ds_write_b16_d16_hi v156, v183 offset:2736
	v_cvt_pk_bf16_f32 v184, v28, v29
	ds_write_b16 v156, v184 offset:3456
	ds_write_b16_d16_hi v156, v184 offset:3600
	v_cvt_pk_bf16_f32 v185, v30, v31
	ds_write_b16 v156, v185 offset:3744
	ds_write_b16_d16_hi v156, v185 offset:3888
	v_cvt_pk_bf16_f32 v182, v0, v1
	ds_write_b16 v156, v182 offset:64
	ds_write_b16_d16_hi v156, v182 offset:208
	v_cvt_pk_bf16_f32 v183, v2, v3
	ds_write_b16 v156, v183 offset:352
	ds_write_b16_d16_hi v156, v183 offset:496
	v_cvt_pk_bf16_f32 v184, v4, v5
	ds_write_b16 v156, v184 offset:1216
	ds_write_b16_d16_hi v156, v184 offset:1360
	v_cvt_pk_bf16_f32 v185, v6, v7
	ds_write_b16 v156, v185 offset:1504
	ds_write_b16_d16_hi v156, v185 offset:1648
	v_cvt_pk_bf16_f32 v182, v8, v9
	ds_write_b16 v156, v182 offset:2368
	ds_write_b16_d16_hi v156, v182 offset:2512
	v_cvt_pk_bf16_f32 v183, v10, v11
	ds_write_b16 v156, v183 offset:2656
	ds_write_b16_d16_hi v156, v183 offset:2800
	v_cvt_pk_bf16_f32 v184, v12, v13
	ds_write_b16 v156, v184 offset:3520
	ds_write_b16_d16_hi v156, v184 offset:3664
	v_cvt_pk_bf16_f32 v185, v14, v15
	ds_write_b16 v156, v185 offset:3808
	ds_write_b16_d16_hi v156, v185 offset:3952
	s_and_saveexec_b64 s[0:1], vcc
	s_cbranch_execz .LBB0_237
	ds_read_b128 v[186:189], v170
	ds_read_b128 v[190:193], v170 offset:1152
	ds_read_b128 v[194:197], v170 offset:2304
	ds_read_b128 v[198:201], v170 offset:3456
	v_or_b32_e32 v6, 0x60, v136
	v_or_b32_e32 v202, v6, v157
	v_mad_i64_i32 v[202:203], s[10:11], v202, s33, v[134:135]
	v_or_b32_e32 v204, v6, v171
	v_mad_i64_i32 v[204:205], s[10:11], v204, s33, v[134:135]
	v_or_b32_e32 v206, v6, v252
	v_mad_i64_i32 v[206:207], s[10:11], v206, s33, v[134:135]
	v_or_b32_e32 v208, v6, v181
	v_mad_i64_i32 v[208:209], s[10:11], v208, s33, v[134:135]
	s_waitcnt lgkmcnt(3)
	global_store_dwordx4 v[202:203], v[186:189], off
	s_waitcnt lgkmcnt(2)
	global_store_dwordx4 v[204:205], v[190:193], off
	s_waitcnt lgkmcnt(1)
	global_store_dwordx4 v[206:207], v[194:197], off
	s_waitcnt lgkmcnt(0)
	global_store_dwordx4 v[208:209], v[198:201], off
	s_branch .LBB0_237

.Lpfg_skip:
	v_add_u32_e32 v130, s1, v179
	s_movk_i32 s1, 0x7fff
	v_ashrrev_i32_e32 v131, 31, v130
	v_cmp_gt_i32_e32 vcc, s1, v130
	v_lshl_add_u64 v[134:135], v[130:131], 1, s[86:87]
	s_nop 5
	v_cvt_pk_bf16_f32 v182, v112, v113
	s_barrier
	ds_write_b16 v156, v182
	ds_write_b16_d16_hi v156, v182 offset:144
	v_cvt_pk_bf16_f32 v183, v114, v115
	ds_write_b16 v156, v183 offset:288
	ds_write_b16_d16_hi v156, v183 offset:432
	v_cvt_pk_bf16_f32 v184, v116, v117
	ds_write_b16 v156, v184 offset:1152
	ds_write_b16_d16_hi v156, v184 offset:1296
	v_cvt_pk_bf16_f32 v185, v118, v119
	ds_write_b16 v156, v185 offset:1440
	ds_write_b16_d16_hi v156, v185 offset:1584
	v_cvt_pk_bf16_f32 v182, v120, v121
	ds_write_b16 v156, v182 offset:2304
	ds_write_b16_d16_hi v156, v182 offset:2448
	v_cvt_pk_bf16_f32 v183, v122, v123
	ds_write_b16 v156, v183 offset:2592
	ds_write_b16_d16_hi v156, v183 offset:2736
	v_cvt_pk_bf16_f32 v184, v124, v125
	ds_write_b16 v156, v184 offset:3456
	ds_write_b16_d16_hi v156, v184 offset:3600
	v_cvt_pk_bf16_f32 v185, v126, v127
	ds_write_b16 v156, v185 offset:3744
	ds_write_b16_d16_hi v156, v185 offset:3888
	v_cvt_pk_bf16_f32 v182, v96, v97
	ds_write_b16 v156, v182 offset:64
	ds_write_b16_d16_hi v156, v182 offset:208
	v_cvt_pk_bf16_f32 v183, v98, v99
	ds_write_b16 v156, v183 offset:352
	ds_write_b16_d16_hi v156, v183 offset:496
	v_cvt_pk_bf16_f32 v184, v100, v101
	ds_write_b16 v156, v184 offset:1216
	ds_write_b16_d16_hi v156, v184 offset:1360
	v_cvt_pk_bf16_f32 v185, v102, v103
	ds_write_b16 v156, v185 offset:1504
	ds_write_b16_d16_hi v156, v185 offset:1648
	v_cvt_pk_bf16_f32 v182, v104, v105
	ds_write_b16 v156, v182 offset:2368
	ds_write_b16_d16_hi v156, v182 offset:2512
	v_cvt_pk_bf16_f32 v183, v106, v107
	ds_write_b16 v156, v183 offset:2656
	ds_write_b16_d16_hi v156, v183 offset:2800
	v_cvt_pk_bf16_f32 v184, v108, v109
	ds_write_b16 v156, v184 offset:3520
	ds_write_b16_d16_hi v156, v184 offset:3664
	v_cvt_pk_bf16_f32 v185, v110, v111
	v_add_u32_e32 v136, s0, v153
	ds_write_b16 v156, v185 offset:3808
	ds_write_b16_d16_hi v156, v185 offset:3952
	s_and_saveexec_b64 s[0:1], vcc
	s_cbranch_execz .Lgo_242
	ds_read_b128 v[186:189], v170
	ds_read_b128 v[190:193], v170 offset:1152
	ds_read_b128 v[194:197], v170 offset:2304
	ds_read_b128 v[198:201], v170 offset:3456
	v_or_b32_e32 v202, v136, v157
	v_mad_i64_i32 v[202:203], s[10:11], v202, s88, v[134:135]
	v_or_b32_e32 v204, v136, v171
	v_mad_i64_i32 v[204:205], s[10:11], v204, s88, v[134:135]
	v_or_b32_e32 v206, v136, v252
	v_mad_i64_i32 v[206:207], s[10:11], v206, s88, v[134:135]
	v_or_b32_e32 v208, v136, v181
	v_mad_i64_i32 v[208:209], s[10:11], v208, s88, v[134:135]
	s_waitcnt lgkmcnt(3)
	global_store_dwordx4 v[202:203], v[186:189], off
	s_waitcnt lgkmcnt(2)
	global_store_dwordx4 v[204:205], v[190:193], off
	s_waitcnt lgkmcnt(1)
	global_store_dwordx4 v[206:207], v[194:197], off
	s_waitcnt lgkmcnt(0)
	global_store_dwordx4 v[208:209], v[198:201], off
.Lgo_242:
	s_or_b64 exec, exec, s[0:1]
	s_nop 0
	v_cvt_pk_bf16_f32 v182, v80, v81
	ds_write_b16 v156, v182
	ds_write_b16_d16_hi v156, v182 offset:144
	v_cvt_pk_bf16_f32 v183, v82, v83
	ds_write_b16 v156, v183 offset:288
	ds_write_b16_d16_hi v156, v183 offset:432
	v_cvt_pk_bf16_f32 v184, v84, v85
	ds_write_b16 v156, v184 offset:1152
	ds_write_b16_d16_hi v156, v184 offset:1296
	v_cvt_pk_bf16_f32 v185, v86, v87
	ds_write_b16 v156, v185 offset:1440
	ds_write_b16_d16_hi v156, v185 offset:1584
	v_cvt_pk_bf16_f32 v182, v88, v89
	ds_write_b16 v156, v182 offset:2304
	ds_write_b16_d16_hi v156, v182 offset:2448
	v_cvt_pk_bf16_f32 v183, v90, v91
	ds_write_b16 v156, v183 offset:2592
	ds_write_b16_d16_hi v156, v183 offset:2736
	v_cvt_pk_bf16_f32 v184, v92, v93
	ds_write_b16 v156, v184 offset:3456
	ds_write_b16_d16_hi v156, v184 offset:3600
	v_cvt_pk_bf16_f32 v185, v94, v95
	ds_write_b16 v156, v185 offset:3744
	ds_write_b16_d16_hi v156, v185 offset:3888
	v_cvt_pk_bf16_f32 v182, v64, v65
	ds_write_b16 v156, v182 offset:64
	ds_write_b16_d16_hi v156, v182 offset:208
	v_cvt_pk_bf16_f32 v183, v66, v67
	ds_write_b16 v156, v183 offset:352
	ds_write_b16_d16_hi v156, v183 offset:496
	v_cvt_pk_bf16_f32 v184, v68, v69
	ds_write_b16 v156, v184 offset:1216
	ds_write_b16_d16_hi v156, v184 offset:1360
	v_cvt_pk_bf16_f32 v185, v70, v71
	ds_write_b16 v156, v185 offset:1504
	ds_write_b16_d16_hi v156, v185 offset:1648
	v_cvt_pk_bf16_f32 v182, v72, v73
	ds_write_b16 v156, v182 offset:2368
	ds_write_b16_d16_hi v156, v182 offset:2512
	v_cvt_pk_bf16_f32 v183, v74, v75
	ds_write_b16 v156, v183 offset:2656
	ds_write_b16_d16_hi v156, v183 offset:2800
	v_cvt_pk_bf16_f32 v184, v76, v77
	ds_write_b16 v156, v184 offset:3520
	ds_write_b16_d16_hi v156, v184 offset:3664
	v_cvt_pk_bf16_f32 v185, v78, v79
	ds_write_b16 v156, v185 offset:3808
	ds_write_b16_d16_hi v156, v185 offset:3952
	s_and_saveexec_b64 s[0:1], vcc
	s_cbranch_execz .Lgo_244
	ds_read_b128 v[186:189], v170
	ds_read_b128 v[190:193], v170 offset:1152
	ds_read_b128 v[194:197], v170 offset:2304
	ds_read_b128 v[198:201], v170 offset:3456
	v_or_b32_e32 v70, 32, v136
	v_or_b32_e32 v202, v70, v157
	v_mad_i64_i32 v[202:203], s[10:11], v202, s88, v[134:135]
	v_or_b32_e32 v204, v70, v171
	v_mad_i64_i32 v[204:205], s[10:11], v204, s88, v[134:135]
	v_or_b32_e32 v206, v70, v252
	v_mad_i64_i32 v[206:207], s[10:11], v206, s88, v[134:135]
	v_or_b32_e32 v208, v70, v181
	v_mad_i64_i32 v[208:209], s[10:11], v208, s88, v[134:135]
	s_waitcnt lgkmcnt(3)
	global_store_dwordx4 v[202:203], v[186:189], off
	s_waitcnt lgkmcnt(2)
	global_store_dwordx4 v[204:205], v[190:193], off
	s_waitcnt lgkmcnt(1)
	global_store_dwordx4 v[206:207], v[194:197], off
	s_waitcnt lgkmcnt(0)
	global_store_dwordx4 v[208:209], v[198:201], off
.Lgo_244:
	s_or_b64 exec, exec, s[0:1]
	s_nop 0
	v_cvt_pk_bf16_f32 v182, v48, v49
	ds_write_b16 v156, v182
	ds_write_b16_d16_hi v156, v182 offset:144
	v_cvt_pk_bf16_f32 v183, v50, v51
	ds_write_b16 v156, v183 offset:288
	ds_write_b16_d16_hi v156, v183 offset:432
	v_cvt_pk_bf16_f32 v184, v52, v53
	ds_write_b16 v156, v184 offset:1152
	ds_write_b16_d16_hi v156, v184 offset:1296
	v_cvt_pk_bf16_f32 v185, v54, v55
	ds_write_b16 v156, v185 offset:1440
	ds_write_b16_d16_hi v156, v185 offset:1584
	v_cvt_pk_bf16_f32 v182, v56, v57
	ds_write_b16 v156, v182 offset:2304
	ds_write_b16_d16_hi v156, v182 offset:2448
	v_cvt_pk_bf16_f32 v183, v58, v59
	ds_write_b16 v156, v183 offset:2592
	ds_write_b16_d16_hi v156, v183 offset:2736
	v_cvt_pk_bf16_f32 v184, v60, v61
	ds_write_b16 v156, v184 offset:3456
	ds_write_b16_d16_hi v156, v184 offset:3600
	v_cvt_pk_bf16_f32 v185, v62, v63
	ds_write_b16 v156, v185 offset:3744
	ds_write_b16_d16_hi v156, v185 offset:3888
	v_cvt_pk_bf16_f32 v182, v32, v33
	ds_write_b16 v156, v182 offset:64
	ds_write_b16_d16_hi v156, v182 offset:208
	v_cvt_pk_bf16_f32 v183, v34, v35
	ds_write_b16 v156, v183 offset:352
	ds_write_b16_d16_hi v156, v183 offset:496
	v_cvt_pk_bf16_f32 v184, v36, v37
	ds_write_b16 v156, v184 offset:1216
	ds_write_b16_d16_hi v156, v184 offset:1360
	v_cvt_pk_bf16_f32 v185, v38, v39
	ds_write_b16 v156, v185 offset:1504
	ds_write_b16_d16_hi v156, v185 offset:1648
	v_cvt_pk_bf16_f32 v182, v40, v41
	ds_write_b16 v156, v182 offset:2368
	ds_write_b16_d16_hi v156, v182 offset:2512
	v_cvt_pk_bf16_f32 v183, v42, v43
	ds_write_b16 v156, v183 offset:2656
	ds_write_b16_d16_hi v156, v183 offset:2800
	v_cvt_pk_bf16_f32 v184, v44, v45
	ds_write_b16 v156, v184 offset:3520
	ds_write_b16_d16_hi v156, v184 offset:3664
	v_cvt_pk_bf16_f32 v185, v46, v47
	ds_write_b16 v156, v185 offset:3808
	ds_write_b16_d16_hi v156, v185 offset:3952
	s_and_saveexec_b64 s[0:1], vcc
	s_cbranch_execz .Lgo_246
	ds_read_b128 v[186:189], v170
	ds_read_b128 v[190:193], v170 offset:1152
	ds_read_b128 v[194:197], v170 offset:2304
	ds_read_b128 v[198:201], v170 offset:3456
	v_or_b32_e32 v38, 64, v136
	v_or_b32_e32 v202, v38, v157
	v_mad_i64_i32 v[202:203], s[10:11], v202, s88, v[134:135]
	v_or_b32_e32 v204, v38, v171
	v_mad_i64_i32 v[204:205], s[10:11], v204, s88, v[134:135]
	v_or_b32_e32 v206, v38, v252
	v_mad_i64_i32 v[206:207], s[10:11], v206, s88, v[134:135]
	v_or_b32_e32 v208, v38, v181
	v_mad_i64_i32 v[208:209], s[10:11], v208, s88, v[134:135]
	s_waitcnt lgkmcnt(3)
	global_store_dwordx4 v[202:203], v[186:189], off
	s_waitcnt lgkmcnt(2)
	global_store_dwordx4 v[204:205], v[190:193], off
	s_waitcnt lgkmcnt(1)
	global_store_dwordx4 v[206:207], v[194:197], off
	s_waitcnt lgkmcnt(0)
	global_store_dwordx4 v[208:209], v[198:201], off
.Lgo_246:
	s_or_b64 exec, exec, s[0:1]
	s_nop 0
	v_cvt_pk_bf16_f32 v182, v16, v17
	ds_write_b16 v156, v182
	ds_write_b16_d16_hi v156, v182 offset:144
	v_cvt_pk_bf16_f32 v183, v18, v19
	ds_write_b16 v156, v183 offset:288
	ds_write_b16_d16_hi v156, v183 offset:432
	v_cvt_pk_bf16_f32 v184, v20, v21
	ds_write_b16 v156, v184 offset:1152
	ds_write_b16_d16_hi v156, v184 offset:1296
	v_cvt_pk_bf16_f32 v185, v22, v23
	ds_write_b16 v156, v185 offset:1440
	ds_write_b16_d16_hi v156, v185 offset:1584
	v_cvt_pk_bf16_f32 v182, v24, v25
	ds_write_b16 v156, v182 offset:2304
	ds_write_b16_d16_hi v156, v182 offset:2448
	v_cvt_pk_bf16_f32 v183, v26, v27
	ds_write_b16 v156, v183 offset:2592
	ds_write_b16_d16_hi v156, v183 offset:2736
	v_cvt_pk_bf16_f32 v184, v28, v29
	ds_write_b16 v156, v184 offset:3456
	ds_write_b16_d16_hi v156, v184 offset:3600
	v_cvt_pk_bf16_f32 v185, v30, v31
	ds_write_b16 v156, v185 offset:3744
	ds_write_b16_d16_hi v156, v185 offset:3888
	v_cvt_pk_bf16_f32 v182, v0, v1
	ds_write_b16 v156, v182 offset:64
	ds_write_b16_d16_hi v156, v182 offset:208
	v_cvt_pk_bf16_f32 v183, v2, v3
	ds_write_b16 v156, v183 offset:352
	ds_write_b16_d16_hi v156, v183 offset:496
	v_cvt_pk_bf16_f32 v184, v4, v5
	ds_write_b16 v156, v184 offset:1216
	ds_write_b16_d16_hi v156, v184 offset:1360
	v_cvt_pk_bf16_f32 v185, v6, v7
	ds_write_b16 v156, v185 offset:1504
	ds_write_b16_d16_hi v156, v185 offset:1648
	v_cvt_pk_bf16_f32 v182, v8, v9
	ds_write_b16 v156, v182 offset:2368
	ds_write_b16_d16_hi v156, v182 offset:2512
	v_cvt_pk_bf16_f32 v183, v10, v11
	ds_write_b16 v156, v183 offset:2656
	ds_write_b16_d16_hi v156, v183 offset:2800
	v_cvt_pk_bf16_f32 v184, v12, v13
	ds_write_b16 v156, v184 offset:3520
	ds_write_b16_d16_hi v156, v184 offset:3664
	v_cvt_pk_bf16_f32 v185, v14, v15
	ds_write_b16 v156, v185 offset:3808
	ds_write_b16_d16_hi v156, v185 offset:3952
	s_and_saveexec_b64 s[0:1], vcc
	s_cbranch_execz .Lgo_237
	ds_read_b128 v[186:189], v170
	ds_read_b128 v[190:193], v170 offset:1152
	ds_read_b128 v[194:197], v170 offset:2304
	ds_read_b128 v[198:201], v170 offset:3456
	v_or_b32_e32 v6, 0x60, v136
	v_or_b32_e32 v202, v6, v157
	v_mad_i64_i32 v[202:203], s[10:11], v202, s88, v[134:135]
	v_or_b32_e32 v204, v6, v171
	v_mad_i64_i32 v[204:205], s[10:11], v204, s88, v[134:135]
	v_or_b32_e32 v206, v6, v252
	v_mad_i64_i32 v[206:207], s[10:11], v206, s88, v[134:135]
	v_or_b32_e32 v208, v6, v181
	v_mad_i64_i32 v[208:209], s[10:11], v208, s88, v[134:135]
	s_waitcnt lgkmcnt(3)
	global_store_dwordx4 v[202:203], v[186:189], off
	s_waitcnt lgkmcnt(2)
	global_store_dwordx4 v[204:205], v[190:193], off
	s_waitcnt lgkmcnt(1)
	global_store_dwordx4 v[206:207], v[194:197], off
	s_waitcnt lgkmcnt(0)
	global_store_dwordx4 v[208:209], v[198:201], off
	s_branch .Lgo_237
